# paired LDS-DMA issue clustered right after MFMA group 2 of even K-steps, plus a per-tile half-step stagger for blocks with blockIdx bit 3
# speedup vs baseline: 1.0090x; 1.0090x over previous
; template <int MI, bool SWAP, class Epi> ...
;     ...
;     for (int kt = 0; kt < nk; ++kt) {
;         if (kt + 1 < nk && !(prefetched && kt == 0)) { if (MI == 8) asm volatile("s_waitcnt vmcnt(6)\n\ts_barrier" ::: "memory"); else if (MI == 4) asm volatile("s_waitcnt vmcnt(4)\n\ts_barrier" ::: "memory"); else asm volatile("s_waitcnt vmcnt(3)\n\ts_barrier" ::: "memory"); }
;         else asm volatile("s_waitcnt vmcnt(0)\n\ts_barrier" ::: "memory");
;         if (kt + 2 < nk) { const int nx = (cur == 0) ? 2 : cur - 1; RING_STAGE(nx, (kt + 2) * 32); }
.Lrp_first_inA:
	v_readlane_b32 vcc_lo, v248, 0
	s_nop 1
	s_bitcmp1_b32 vcc_lo, 3
	s_cbranch_scc0 .Lrp_nostag0_inA
	s_sleep 9

; __device__ __forceinline__ f32x4 mfma16(bf16x8 a, bf16x8 b, f32x4 c) { return __builtin_amdgcn_mfma_f32_16x16x32_bf16(a, b, c, 0, 0, 0); }
; template <int MI, bool SWAP, class Epi> ...
;     ...
; #pragma unroll
;         for (int i = 0; i < MI; ++i) {
; #pragma unroll
;             for (int j = 0; j < 4; ++j) {
;                 if (SWAP) acc[i][j] = mfma16(bf[j], af[i], acc[i][j]);
;                 else acc[i][j] = mfma16(af[i], bf[j], acc[i][j]);
;             }
;         }
.Lrp_go_inA_e:
	s_sub_i32 vcc_lo, s8, s9
	v_mfma_f32_16x16x32_bf16 v[124:127], v[128:131], v[172:175], v[124:127]
	v_mfma_f32_16x16x32_bf16 v[120:123], v[132:135], v[172:175], v[120:123]
	v_mfma_f32_16x16x32_bf16 v[116:119], v[136:139], v[172:175], v[116:119]
	v_mfma_f32_16x16x32_bf16 v[112:115], v[140:143], v[172:175], v[112:115]
	v_mfma_f32_16x16x32_bf16 v[108:111], v[128:131], v[168:171], v[108:111]
	v_mfma_f32_16x16x32_bf16 v[104:107], v[132:135], v[168:171], v[104:107]
	v_mfma_f32_16x16x32_bf16 v[100:103], v[136:139], v[168:171], v[100:103]
	v_mfma_f32_16x16x32_bf16 v[96:99], v[140:143], v[168:171], v[96:99]
	v_mfma_f32_16x16x32_bf16 v[92:95], v[128:131], v[164:167], v[92:95]
	v_mfma_f32_16x16x32_bf16 v[88:91], v[132:135], v[164:167], v[88:91]
	v_mfma_f32_16x16x32_bf16 v[84:87], v[136:139], v[164:167], v[84:87]
	v_mfma_f32_16x16x32_bf16 v[80:83], v[140:143], v[164:167], v[80:83]
	v_lshl_add_u64 v[172:173], v[178:179], 0, s[6:7]
	s_add_i32 s29, s9, s11
	s_mov_b32 m0, s29
	v_lshl_add_u64 v[168:169], v[172:173], 0, 64
	global_load_lds_dwordx4 v[172:173], off
	s_add_i32 m0, s29, vcc_lo
	s_nop 0
	global_load_lds_dwordx4 v[168:169], off
	s_mov_b64 s[38:39], 0x8000
	v_lshl_add_u64 v[174:175], v[172:173], 0, s[38:39]
	s_add_i32 s30, s29, 0x400
	s_mov_b32 m0, s30
	v_lshl_add_u64 v[168:169], v[174:175], 0, 64
	global_load_lds_dwordx4 v[174:175], off
	s_add_i32 m0, s30, vcc_lo
	s_nop 0
	global_load_lds_dwordx4 v[168:169], off
	s_mov_b64 s[30:31], 0x10000
	v_lshl_add_u64 v[174:175], v[172:173], 0, s[30:31]
	s_add_i32 s30, s29, 0x800
	s_mov_b32 m0, s30
	v_lshl_add_u64 v[168:169], v[174:175], 0, 64
	global_load_lds_dwordx4 v[174:175], off
	s_add_i32 m0, s30, vcc_lo
	s_nop 0
	global_load_lds_dwordx4 v[168:169], off
	s_mov_b64 s[30:31], 0x18000
	v_lshl_add_u64 v[172:173], v[172:173], 0, s[30:31]
	s_addk_i32 s29, 0xc00
	s_mov_b32 m0, s29
	v_lshl_add_u64 v[168:169], v[172:173], 0, 64
	global_load_lds_dwordx4 v[172:173], off
	s_add_i32 m0, s29, vcc_lo
	s_nop 0
	global_load_lds_dwordx4 v[168:169], off
	v_lshl_add_u64 v[172:173], v[176:177], 0, s[6:7]
	s_add_i32 s9, s9, s22
	s_mov_b32 m0, s9
	v_lshl_add_u64 v[168:169], v[172:173], 0, 64
	global_load_lds_dwordx4 v[172:173], off
	s_add_i32 m0, s9, vcc_lo
	s_nop 0
	global_load_lds_dwordx4 v[168:169], off
	v_lshl_add_u64 v[172:173], v[172:173], 0, s[38:39]
	s_addk_i32 s9, 0x400
	s_mov_b32 m0, s9
	v_lshl_add_u64 v[168:169], v[172:173], 0, 64
	global_load_lds_dwordx4 v[172:173], off
	s_add_i32 m0, s9, vcc_lo
	s_nop 0
	global_load_lds_dwordx4 v[168:169], off
	v_mfma_f32_16x16x32_bf16 v[76:79], v[128:131], v[160:163], v[76:79]
	v_mfma_f32_16x16x32_bf16 v[72:75], v[132:135], v[160:163], v[72:75]
	v_mfma_f32_16x16x32_bf16 v[68:71], v[136:139], v[160:163], v[68:71]
	v_mfma_f32_16x16x32_bf16 v[64:67], v[140:143], v[160:163], v[64:67]
	v_mfma_f32_16x16x32_bf16 v[60:63], v[128:131], v[156:159], v[60:63]
	v_mfma_f32_16x16x32_bf16 v[56:59], v[132:135], v[156:159], v[56:59]
	v_mfma_f32_16x16x32_bf16 v[52:55], v[136:139], v[156:159], v[52:55]
	v_mfma_f32_16x16x32_bf16 v[48:51], v[140:143], v[156:159], v[48:51]
	v_mfma_f32_16x16x32_bf16 v[44:47], v[128:131], v[152:155], v[44:47]
	v_mfma_f32_16x16x32_bf16 v[40:43], v[132:135], v[152:155], v[40:43]
	v_mfma_f32_16x16x32_bf16 v[36:39], v[136:139], v[152:155], v[36:39]
	v_mfma_f32_16x16x32_bf16 v[32:35], v[140:143], v[152:155], v[32:35]
	v_mfma_f32_16x16x32_bf16 v[28:31], v[128:131], v[148:151], v[28:31]
	v_mfma_f32_16x16x32_bf16 v[24:27], v[132:135], v[148:151], v[24:27]
	v_mfma_f32_16x16x32_bf16 v[20:23], v[136:139], v[148:151], v[20:23]
	v_mfma_f32_16x16x32_bf16 v[16:19], v[140:143], v[148:151], v[16:19]
	v_mfma_f32_16x16x32_bf16 v[12:15], v[128:131], v[144:147], v[12:15]
	v_mfma_f32_16x16x32_bf16 v[8:11], v[132:135], v[144:147], v[8:11]
	v_mfma_f32_16x16x32_bf16 v[4:7], v[136:139], v[144:147], v[4:7]
	v_mfma_f32_16x16x32_bf16 v[0:3], v[140:143], v[144:147], v[0:3]

; __device__ __forceinline__ f32x4 mfma16(bf16x8 a, bf16x8 b, f32x4 c) { return __builtin_amdgcn_mfma_f32_16x16x32_bf16(a, b, c, 0, 0, 0); }
; template <int MI, bool SWAP, class Epi> ...
;     ...
; #pragma unroll
;         for (int i = 0; i < MI; ++i) {
; #pragma unroll
;             for (int j = 0; j < 4; ++j) {
;                 if (SWAP) acc[i][j] = mfma16(bf[j], af[i], acc[i][j]);
;                 else acc[i][j] = mfma16(af[i], bf[j], acc[i][j]);
;             }
;         }
.Lrp_go_inB_e:
	s_sub_i32 vcc_lo, s6, s7
	v_mfma_f32_16x16x32_bf16 v[124:127], v[172:175], v[128:131], v[124:127]
	v_mfma_f32_16x16x32_bf16 v[120:123], v[172:175], v[132:135], v[120:123]
	v_mfma_f32_16x16x32_bf16 v[116:119], v[172:175], v[136:139], v[116:119]
	v_mfma_f32_16x16x32_bf16 v[112:115], v[172:175], v[140:143], v[112:115]
	v_mfma_f32_16x16x32_bf16 v[108:111], v[168:171], v[128:131], v[108:111]
	v_mfma_f32_16x16x32_bf16 v[104:107], v[168:171], v[132:135], v[104:107]
	v_mfma_f32_16x16x32_bf16 v[100:103], v[168:171], v[136:139], v[100:103]
	v_mfma_f32_16x16x32_bf16 v[96:99], v[168:171], v[140:143], v[96:99]
	v_mfma_f32_16x16x32_bf16 v[92:95], v[164:167], v[128:131], v[92:95]
	v_mfma_f32_16x16x32_bf16 v[88:91], v[164:167], v[132:135], v[88:91]
	v_mfma_f32_16x16x32_bf16 v[84:87], v[164:167], v[136:139], v[84:87]
	v_mfma_f32_16x16x32_bf16 v[80:83], v[164:167], v[140:143], v[80:83]
	v_lshl_add_u64 v[172:173], v[178:179], 0, s[4:5]
	s_add_i32 s23, s7, s9
	s_mov_b32 m0, s23
	v_lshl_add_u64 v[168:169], v[172:173], 0, 64
	global_load_lds_dwordx4 v[172:173], off
	s_add_i32 m0, s23, vcc_lo
	s_nop 0
	global_load_lds_dwordx4 v[168:169], off
	s_mov_b64 s[30:31], 0x8000
	v_lshl_add_u64 v[174:175], v[172:173], 0, s[30:31]
	s_add_i32 s24, s23, 0x400
	s_mov_b32 m0, s24
	v_lshl_add_u64 v[168:169], v[174:175], 0, 64
	global_load_lds_dwordx4 v[174:175], off
	s_add_i32 m0, s24, vcc_lo
	s_nop 0
	global_load_lds_dwordx4 v[168:169], off
	s_mov_b64 s[24:25], 0x10000
	v_lshl_add_u64 v[174:175], v[172:173], 0, s[24:25]
	s_add_i32 s24, s23, 0x800
	s_mov_b32 m0, s24
	v_lshl_add_u64 v[168:169], v[174:175], 0, 64
	global_load_lds_dwordx4 v[174:175], off
	s_add_i32 m0, s24, vcc_lo
	s_nop 0
	global_load_lds_dwordx4 v[168:169], off
	s_mov_b64 s[24:25], 0x18000
	v_lshl_add_u64 v[172:173], v[172:173], 0, s[24:25]
	s_addk_i32 s23, 0xc00
	s_mov_b32 m0, s23
	v_lshl_add_u64 v[168:169], v[172:173], 0, 64
	global_load_lds_dwordx4 v[172:173], off
	s_add_i32 m0, s23, vcc_lo
	s_nop 0
	global_load_lds_dwordx4 v[168:169], off
	v_lshl_add_u64 v[172:173], v[176:177], 0, s[4:5]
	s_add_i32 s7, s7, s10
	s_mov_b32 m0, s7
	v_lshl_add_u64 v[168:169], v[172:173], 0, 64
	global_load_lds_dwordx4 v[172:173], off
	s_add_i32 m0, s7, vcc_lo
	s_nop 0
	global_load_lds_dwordx4 v[168:169], off
	v_lshl_add_u64 v[172:173], v[172:173], 0, s[30:31]
	s_addk_i32 s7, 0x400
	s_mov_b32 m0, s7
	v_lshl_add_u64 v[168:169], v[172:173], 0, 64
	global_load_lds_dwordx4 v[172:173], off
	s_add_i32 m0, s7, vcc_lo
	s_nop 0
	global_load_lds_dwordx4 v[168:169], off
	v_mfma_f32_16x16x32_bf16 v[76:79], v[160:163], v[128:131], v[76:79]
	v_mfma_f32_16x16x32_bf16 v[72:75], v[160:163], v[132:135], v[72:75]
	v_mfma_f32_16x16x32_bf16 v[68:71], v[160:163], v[136:139], v[68:71]
	v_mfma_f32_16x16x32_bf16 v[64:67], v[160:163], v[140:143], v[64:67]
	v_mfma_f32_16x16x32_bf16 v[60:63], v[156:159], v[128:131], v[60:63]
	v_mfma_f32_16x16x32_bf16 v[56:59], v[156:159], v[132:135], v[56:59]
	v_mfma_f32_16x16x32_bf16 v[52:55], v[156:159], v[136:139], v[52:55]
	v_mfma_f32_16x16x32_bf16 v[48:51], v[156:159], v[140:143], v[48:51]
	v_mfma_f32_16x16x32_bf16 v[44:47], v[152:155], v[128:131], v[44:47]
	v_mfma_f32_16x16x32_bf16 v[40:43], v[152:155], v[132:135], v[40:43]
	v_mfma_f32_16x16x32_bf16 v[36:39], v[152:155], v[136:139], v[36:39]
	v_mfma_f32_16x16x32_bf16 v[32:35], v[152:155], v[140:143], v[32:35]
	v_mfma_f32_16x16x32_bf16 v[28:31], v[148:151], v[128:131], v[28:31]
	v_mfma_f32_16x16x32_bf16 v[24:27], v[148:151], v[132:135], v[24:27]
	v_mfma_f32_16x16x32_bf16 v[20:23], v[148:151], v[136:139], v[20:23]
	v_mfma_f32_16x16x32_bf16 v[16:19], v[148:151], v[140:143], v[16:19]
	v_mfma_f32_16x16x32_bf16 v[12:15], v[144:147], v[128:131], v[12:15]
	v_mfma_f32_16x16x32_bf16 v[8:11], v[144:147], v[132:135], v[8:11]
	v_mfma_f32_16x16x32_bf16 v[4:7], v[144:147], v[136:139], v[4:7]
	v_mfma_f32_16x16x32_bf16 v[0:3], v[144:147], v[140:143], v[0:3]

; __device__ __forceinline__ f32x4 mfma16(bf16x8 a, bf16x8 b, f32x4 c) { return __builtin_amdgcn_mfma_f32_16x16x32_bf16(a, b, c, 0, 0, 0); }
; template <int MI, bool SWAP, class Epi> ...
;     ...
; #pragma unroll
;         for (int i = 0; i < MI; ++i) {
; #pragma unroll
;             for (int j = 0; j < 4; ++j) {
;                 if (SWAP) acc[i][j] = mfma16(bf[j], af[i], acc[i][j]);
;                 else acc[i][j] = mfma16(af[i], bf[j], acc[i][j]);
;             }
;         }
.Lrp_go_outp_e:
	s_sub_i32 vcc_lo, s8, s9
	v_mfma_f32_16x16x32_bf16 v[120:123], v[128:131], v[172:175], v[120:123]
	v_mfma_f32_16x16x32_bf16 v[116:119], v[132:135], v[172:175], v[116:119]
	v_mfma_f32_16x16x32_bf16 v[112:115], v[136:139], v[172:175], v[112:115]
	v_mfma_f32_16x16x32_bf16 v[108:111], v[140:143], v[172:175], v[108:111]
	v_mfma_f32_16x16x32_bf16 v[104:107], v[128:131], v[168:171], v[104:107]
	v_mfma_f32_16x16x32_bf16 v[100:103], v[132:135], v[168:171], v[100:103]
	v_mfma_f32_16x16x32_bf16 v[96:99], v[136:139], v[168:171], v[96:99]
	v_mfma_f32_16x16x32_bf16 v[92:95], v[140:143], v[168:171], v[92:95]
	v_mfma_f32_16x16x32_bf16 v[88:91], v[128:131], v[164:167], v[88:91]
	v_mfma_f32_16x16x32_bf16 v[84:87], v[132:135], v[164:167], v[84:87]
	v_mfma_f32_16x16x32_bf16 v[80:83], v[136:139], v[164:167], v[80:83]
	v_mfma_f32_16x16x32_bf16 v[76:79], v[140:143], v[164:167], v[76:79]
	v_lshl_add_u64 v[172:173], v[178:179], 0, s[6:7]
	s_add_i32 s29, s9, s24
	s_mov_b32 m0, s29
	v_lshl_add_u64 v[168:169], v[172:173], 0, 64
	global_load_lds_dwordx4 v[172:173], off
	s_add_i32 m0, s29, vcc_lo
	s_nop 0
	global_load_lds_dwordx4 v[168:169], off
	s_mov_b64 s[34:35], 0x8000
	v_lshl_add_u64 v[174:175], v[172:173], 0, s[34:35]
	s_add_i32 s30, s29, 0x400
	s_mov_b32 m0, s30
	v_lshl_add_u64 v[168:169], v[174:175], 0, 64
	global_load_lds_dwordx4 v[174:175], off
	s_add_i32 m0, s30, vcc_lo
	s_nop 0
	global_load_lds_dwordx4 v[168:169], off
	s_mov_b64 s[30:31], 0x10000
	v_lshl_add_u64 v[174:175], v[172:173], 0, s[30:31]
	s_add_i32 s30, s29, 0x800
	s_mov_b32 m0, s30
	v_lshl_add_u64 v[168:169], v[174:175], 0, 64
	global_load_lds_dwordx4 v[174:175], off
	s_add_i32 m0, s30, vcc_lo
	s_nop 0
	global_load_lds_dwordx4 v[168:169], off
	s_mov_b64 s[30:31], 0x18000
	v_lshl_add_u64 v[172:173], v[172:173], 0, s[30:31]
	s_addk_i32 s29, 0xc00
	s_mov_b32 m0, s29
	v_lshl_add_u64 v[168:169], v[172:173], 0, 64
	global_load_lds_dwordx4 v[172:173], off
	s_add_i32 m0, s29, vcc_lo
	s_nop 0
	global_load_lds_dwordx4 v[168:169], off
	v_lshl_add_u64 v[172:173], v[176:177], 0, s[6:7]
	s_add_i32 s9, s9, s25
	s_mov_b32 m0, s9
	v_lshl_add_u64 v[168:169], v[172:173], 0, 64
	global_load_lds_dwordx4 v[172:173], off
	s_add_i32 m0, s9, vcc_lo
	s_nop 0
	global_load_lds_dwordx4 v[168:169], off
	v_lshl_add_u64 v[172:173], v[172:173], 0, s[34:35]
	s_addk_i32 s9, 0x400
	s_mov_b32 m0, s9
	v_lshl_add_u64 v[168:169], v[172:173], 0, 64
	global_load_lds_dwordx4 v[172:173], off
	s_add_i32 m0, s9, vcc_lo
	s_nop 0
	global_load_lds_dwordx4 v[168:169], off
	v_mfma_f32_16x16x32_bf16 v[72:75], v[128:131], v[160:163], v[72:75]
	v_mfma_f32_16x16x32_bf16 v[68:71], v[132:135], v[160:163], v[68:71]
	v_mfma_f32_16x16x32_bf16 v[64:67], v[136:139], v[160:163], v[64:67]
	v_mfma_f32_16x16x32_bf16 v[60:63], v[140:143], v[160:163], v[60:63]
	v_mfma_f32_16x16x32_bf16 v[56:59], v[128:131], v[156:159], v[56:59]
	v_mfma_f32_16x16x32_bf16 v[52:55], v[132:135], v[156:159], v[52:55]
	v_mfma_f32_16x16x32_bf16 v[48:51], v[136:139], v[156:159], v[48:51]
	v_mfma_f32_16x16x32_bf16 v[44:47], v[140:143], v[156:159], v[44:47]
	v_mfma_f32_16x16x32_bf16 v[40:43], v[128:131], v[152:155], v[40:43]
	v_mfma_f32_16x16x32_bf16 v[36:39], v[132:135], v[152:155], v[36:39]
	v_mfma_f32_16x16x32_bf16 v[32:35], v[136:139], v[152:155], v[32:35]
	v_mfma_f32_16x16x32_bf16 v[28:31], v[140:143], v[152:155], v[28:31]
	v_mfma_f32_16x16x32_bf16 v[24:27], v[128:131], v[148:151], v[24:27]
	v_mfma_f32_16x16x32_bf16 v[20:23], v[132:135], v[148:151], v[20:23]
	v_mfma_f32_16x16x32_bf16 v[16:19], v[136:139], v[148:151], v[16:19]
	v_mfma_f32_16x16x32_bf16 v[12:15], v[140:143], v[148:151], v[12:15]
	v_mfma_f32_16x16x32_bf16 v[8:11], v[128:131], v[144:147], v[8:11]
	v_mfma_f32_16x16x32_bf16 v[4:7], v[132:135], v[144:147], v[4:7]
	v_mfma_f32_16x16x32_bf16 v[0:3], v[136:139], v[144:147], v[0:3]
	v_mfma_f32_16x16x32_bf16 v[124:127], v[140:143], v[144:147], v[124:127]

; __device__ __forceinline__ f32x4 mfma16(bf16x8 a, bf16x8 b, f32x4 c) { return __builtin_amdgcn_mfma_f32_16x16x32_bf16(a, b, c, 0, 0, 0); }
; template <int MI, bool SWAP, class Epi> ...
;     ...
; #pragma unroll
;         for (int i = 0; i < MI; ++i) {
; #pragma unroll
;             for (int j = 0; j < 4; ++j) {
;                 if (SWAP) acc[i][j] = mfma16(bf[j], af[i], acc[i][j]);
;                 else acc[i][j] = mfma16(af[i], bf[j], acc[i][j]);
;             }
;         }
.Lrp_go_ff1_e:
	s_sub_i32 vcc_lo, s8, s9
	v_mfma_f32_16x16x32_bf16 v[120:123], v[128:131], v[172:175], v[120:123]
	v_mfma_f32_16x16x32_bf16 v[116:119], v[132:135], v[172:175], v[116:119]
	v_mfma_f32_16x16x32_bf16 v[112:115], v[136:139], v[172:175], v[112:115]
	v_mfma_f32_16x16x32_bf16 v[108:111], v[140:143], v[172:175], v[108:111]
	v_mfma_f32_16x16x32_bf16 v[104:107], v[128:131], v[168:171], v[104:107]
	v_mfma_f32_16x16x32_bf16 v[100:103], v[132:135], v[168:171], v[100:103]
	v_mfma_f32_16x16x32_bf16 v[96:99], v[136:139], v[168:171], v[96:99]
	v_mfma_f32_16x16x32_bf16 v[92:95], v[140:143], v[168:171], v[92:95]
	v_mfma_f32_16x16x32_bf16 v[88:91], v[128:131], v[164:167], v[88:91]
	v_mfma_f32_16x16x32_bf16 v[84:87], v[132:135], v[164:167], v[84:87]
	v_mfma_f32_16x16x32_bf16 v[80:83], v[136:139], v[164:167], v[80:83]
	v_mfma_f32_16x16x32_bf16 v[76:79], v[140:143], v[164:167], v[76:79]
	v_lshl_add_u64 v[172:173], v[178:179], 0, s[6:7]
	s_add_i32 s28, s9, s23
	s_mov_b32 m0, s28
	v_lshl_add_u64 v[168:169], v[172:173], 0, 64
	global_load_lds_dwordx4 v[172:173], off
	s_add_i32 m0, s28, vcc_lo
	s_nop 0
	global_load_lds_dwordx4 v[168:169], off
	s_mov_b64 s[12:13], 0x8000
	v_lshl_add_u64 v[174:175], v[172:173], 0, s[12:13]
	s_add_i32 s29, s28, 0x400
	s_mov_b32 m0, s29
	v_lshl_add_u64 v[168:169], v[174:175], 0, 64
	global_load_lds_dwordx4 v[174:175], off
	s_add_i32 m0, s29, vcc_lo
	s_nop 0
	global_load_lds_dwordx4 v[168:169], off
	s_mov_b64 s[14:15], 0x10000
	v_lshl_add_u64 v[174:175], v[172:173], 0, s[14:15]
	s_add_i32 s29, s28, 0x800
	s_mov_b32 m0, s29
	v_lshl_add_u64 v[168:169], v[174:175], 0, 64
	global_load_lds_dwordx4 v[174:175], off
	s_add_i32 m0, s29, vcc_lo
	s_nop 0
	global_load_lds_dwordx4 v[168:169], off
	s_mov_b64 s[14:15], 0x18000
	v_lshl_add_u64 v[172:173], v[172:173], 0, s[14:15]
	s_addk_i32 s28, 0xc00
	s_mov_b32 m0, s28
	v_lshl_add_u64 v[168:169], v[172:173], 0, 64
	global_load_lds_dwordx4 v[172:173], off
	s_add_i32 m0, s28, vcc_lo
	s_nop 0
	global_load_lds_dwordx4 v[168:169], off
	v_lshl_add_u64 v[172:173], v[176:177], 0, s[6:7]
	s_add_i32 s9, s9, s24
	s_mov_b32 m0, s9
	v_lshl_add_u64 v[168:169], v[172:173], 0, 64
	global_load_lds_dwordx4 v[172:173], off
	s_add_i32 m0, s9, vcc_lo
	s_nop 0
	global_load_lds_dwordx4 v[168:169], off
	v_lshl_add_u64 v[172:173], v[172:173], 0, s[12:13]
	s_addk_i32 s9, 0x400
	s_mov_b32 m0, s9
	v_lshl_add_u64 v[168:169], v[172:173], 0, 64
	global_load_lds_dwordx4 v[172:173], off
	s_add_i32 m0, s9, vcc_lo
	s_nop 0
	global_load_lds_dwordx4 v[168:169], off
	v_mfma_f32_16x16x32_bf16 v[72:75], v[128:131], v[160:163], v[72:75]
	v_mfma_f32_16x16x32_bf16 v[68:71], v[132:135], v[160:163], v[68:71]
	v_mfma_f32_16x16x32_bf16 v[64:67], v[136:139], v[160:163], v[64:67]
	v_mfma_f32_16x16x32_bf16 v[60:63], v[140:143], v[160:163], v[60:63]
	v_mfma_f32_16x16x32_bf16 v[56:59], v[128:131], v[156:159], v[56:59]
	v_mfma_f32_16x16x32_bf16 v[52:55], v[132:135], v[156:159], v[52:55]
	v_mfma_f32_16x16x32_bf16 v[48:51], v[136:139], v[156:159], v[48:51]
	v_mfma_f32_16x16x32_bf16 v[44:47], v[140:143], v[156:159], v[44:47]
	v_mfma_f32_16x16x32_bf16 v[40:43], v[128:131], v[152:155], v[40:43]
	v_mfma_f32_16x16x32_bf16 v[36:39], v[132:135], v[152:155], v[36:39]
	v_mfma_f32_16x16x32_bf16 v[32:35], v[136:139], v[152:155], v[32:35]
	v_mfma_f32_16x16x32_bf16 v[28:31], v[140:143], v[152:155], v[28:31]
	v_mfma_f32_16x16x32_bf16 v[24:27], v[128:131], v[148:151], v[24:27]
	v_mfma_f32_16x16x32_bf16 v[20:23], v[132:135], v[148:151], v[20:23]
	v_mfma_f32_16x16x32_bf16 v[16:19], v[136:139], v[148:151], v[16:19]
	v_mfma_f32_16x16x32_bf16 v[12:15], v[140:143], v[148:151], v[12:15]
	v_mfma_f32_16x16x32_bf16 v[8:11], v[128:131], v[144:147], v[8:11]
	v_mfma_f32_16x16x32_bf16 v[4:7], v[132:135], v[144:147], v[4:7]
	v_mfma_f32_16x16x32_bf16 v[0:3], v[136:139], v[144:147], v[0:3]
	v_mfma_f32_16x16x32_bf16 v[124:127], v[140:143], v[144:147], v[124:127]

; __device__ __forceinline__ f32x4 mfma16(bf16x8 a, bf16x8 b, f32x4 c) { return __builtin_amdgcn_mfma_f32_16x16x32_bf16(a, b, c, 0, 0, 0); }
; template <int MI, bool SWAP, class Epi> ...
;     ...
; #pragma unroll
;         for (int i = 0; i < MI; ++i) {
; #pragma unroll
;             for (int j = 0; j < 4; ++j) {
;                 if (SWAP) acc[i][j] = mfma16(bf[j], af[i], acc[i][j]);
;                 else acc[i][j] = mfma16(af[i], bf[j], acc[i][j]);
;             }
;         }
.Lrp_go_ff2_e:
	s_sub_i32 vcc_lo, s8, s9
	v_mfma_f32_16x16x32_bf16 v[120:123], v[128:131], v[172:175], v[120:123]
	v_mfma_f32_16x16x32_bf16 v[116:119], v[132:135], v[172:175], v[116:119]
	v_mfma_f32_16x16x32_bf16 v[112:115], v[136:139], v[172:175], v[112:115]
	v_mfma_f32_16x16x32_bf16 v[108:111], v[140:143], v[172:175], v[108:111]
	v_mfma_f32_16x16x32_bf16 v[104:107], v[128:131], v[168:171], v[104:107]
	v_mfma_f32_16x16x32_bf16 v[100:103], v[132:135], v[168:171], v[100:103]
	v_mfma_f32_16x16x32_bf16 v[96:99], v[136:139], v[168:171], v[96:99]
	v_mfma_f32_16x16x32_bf16 v[92:95], v[140:143], v[168:171], v[92:95]
	v_mfma_f32_16x16x32_bf16 v[88:91], v[128:131], v[164:167], v[88:91]
	v_mfma_f32_16x16x32_bf16 v[84:87], v[132:135], v[164:167], v[84:87]
	v_mfma_f32_16x16x32_bf16 v[80:83], v[136:139], v[164:167], v[80:83]
	v_mfma_f32_16x16x32_bf16 v[76:79], v[140:143], v[164:167], v[76:79]
	v_lshl_add_u64 v[172:173], v[178:179], 0, s[6:7]
	s_add_i32 s31, s9, s26
	s_mov_b32 m0, s31
	v_lshl_add_u64 v[168:169], v[172:173], 0, 64
	global_load_lds_dwordx4 v[172:173], off
	s_add_i32 m0, s31, vcc_lo
	s_nop 0
	global_load_lds_dwordx4 v[168:169], off
	s_mov_b64 s[12:13], 0x20000
	v_lshl_add_u64 v[174:175], v[172:173], 0, s[12:13]
	s_add_i32 s34, s31, 0x400
	s_mov_b32 m0, s34
	v_lshl_add_u64 v[168:169], v[174:175], 0, 64
	global_load_lds_dwordx4 v[174:175], off
	s_add_i32 m0, s34, vcc_lo
	s_nop 0
	global_load_lds_dwordx4 v[168:169], off
	s_mov_b64 s[34:35], 0x40000
	v_lshl_add_u64 v[174:175], v[172:173], 0, s[34:35]
	s_add_i32 s34, s31, 0x800
	s_mov_b32 m0, s34
	v_lshl_add_u64 v[168:169], v[174:175], 0, 64
	global_load_lds_dwordx4 v[174:175], off
	s_add_i32 m0, s34, vcc_lo
	s_nop 0
	global_load_lds_dwordx4 v[168:169], off
	s_mov_b64 s[34:35], 0x60000
	v_lshl_add_u64 v[172:173], v[172:173], 0, s[34:35]
	s_addk_i32 s31, 0xc00
	s_mov_b32 m0, s31
	v_lshl_add_u64 v[168:169], v[172:173], 0, 64
	global_load_lds_dwordx4 v[172:173], off
	s_add_i32 m0, s31, vcc_lo
	s_nop 0
	global_load_lds_dwordx4 v[168:169], off
	v_lshl_add_u64 v[172:173], v[176:177], 0, s[6:7]
	s_add_i32 s9, s9, s27
	s_mov_b32 m0, s9
	v_lshl_add_u64 v[168:169], v[172:173], 0, 64
	global_load_lds_dwordx4 v[172:173], off
	s_add_i32 m0, s9, vcc_lo
	s_nop 0
	global_load_lds_dwordx4 v[168:169], off
	v_lshl_add_u64 v[172:173], v[172:173], 0, s[12:13]
	s_addk_i32 s9, 0x400
	s_mov_b32 m0, s9
	v_lshl_add_u64 v[168:169], v[172:173], 0, 64
	global_load_lds_dwordx4 v[172:173], off
	s_add_i32 m0, s9, vcc_lo
	s_nop 0
	global_load_lds_dwordx4 v[168:169], off
	v_mfma_f32_16x16x32_bf16 v[72:75], v[128:131], v[160:163], v[72:75]
	v_mfma_f32_16x16x32_bf16 v[68:71], v[132:135], v[160:163], v[68:71]
	v_mfma_f32_16x16x32_bf16 v[64:67], v[136:139], v[160:163], v[64:67]
	v_mfma_f32_16x16x32_bf16 v[60:63], v[140:143], v[160:163], v[60:63]
	v_mfma_f32_16x16x32_bf16 v[56:59], v[128:131], v[156:159], v[56:59]
	v_mfma_f32_16x16x32_bf16 v[52:55], v[132:135], v[156:159], v[52:55]
	v_mfma_f32_16x16x32_bf16 v[48:51], v[136:139], v[156:159], v[48:51]
	v_mfma_f32_16x16x32_bf16 v[44:47], v[140:143], v[156:159], v[44:47]
	v_mfma_f32_16x16x32_bf16 v[40:43], v[128:131], v[152:155], v[40:43]
	v_mfma_f32_16x16x32_bf16 v[36:39], v[132:135], v[152:155], v[36:39]
	v_mfma_f32_16x16x32_bf16 v[32:35], v[136:139], v[152:155], v[32:35]
	v_mfma_f32_16x16x32_bf16 v[28:31], v[140:143], v[152:155], v[28:31]
	v_mfma_f32_16x16x32_bf16 v[24:27], v[128:131], v[148:151], v[24:27]
	v_mfma_f32_16x16x32_bf16 v[20:23], v[132:135], v[148:151], v[20:23]
	v_mfma_f32_16x16x32_bf16 v[16:19], v[136:139], v[148:151], v[16:19]
	v_mfma_f32_16x16x32_bf16 v[12:15], v[140:143], v[148:151], v[12:15]
	v_mfma_f32_16x16x32_bf16 v[8:11], v[128:131], v[144:147], v[8:11]
	v_mfma_f32_16x16x32_bf16 v[4:7], v[132:135], v[144:147], v[4:7]
	v_mfma_f32_16x16x32_bf16 v[0:3], v[136:139], v[144:147], v[0:3]
	v_mfma_f32_16x16x32_bf16 v[124:127], v[140:143], v[144:147], v[124:127]
